# v18 + memory-attention pass-B poll/invalidate by thread 0 only (group barrier orders the other attention waves behind it)
# speedup vs baseline: 1.0349x; 1.0002x over previous
; #define GROUP_LOOP(qi, total, ...) for (int gi_ = 0;; ++gi_) { if (threadIdx.x == 0) ctlw[22 + (gi_ & 1)] = __hip_atomic_fetch_add(qbase + 64 * (qi), 1u, __ATOMIC_RELAXED, __HIP_MEMORY_SCOPE_AGENT); \
;         group_bar(gb, lane); const int u = (int)ctlw[22 + (gi_ & 1)]; if (u >= (total)) break; __VA_ARGS__ }
; template <int MASK> __device__ __forceinline__ void phase3(const Params& p, LAS unsigned char* lds, volatile LAS unsigned* ctlw, int qset) {
;     ...
;             GROUP_LOOP(3, U_MEMP + U_MEMS, {
;                 if (u < U_MEMP) { const int hm = u & 3, qb = (u >> 2) & 15, b = u >> 6; const size_t r0 = (size_t)(b * SEQ + qb * 128);
;                     attn_unit<1>(lds, gb, PROJ + r0 * NPAD + PC_MQ + hm * 128, NPAD, (const bf16_t*)(p.ws + WS_MKN) + (size_t)(b * MEMT) * 512 + hm * 128, (const bf16_t*)(p.ws + WS_MVB) + (size_t)(b * MEMT) * 512 + hm * 128, 512,
;                                  4, 0, 128, 0.f, PROJ + r0 * NPAD + PC_GM + hm * 128, NPAD, MIX + r0 * 2048 + 1536 + hm * 128, 2048); }
;                 else { const int v = u - U_MEMP, hm = v & 3, sq = v >> 2; const size_t r0 = (size_t)(MP + sq * DTOK);
;                     attn_unit<1>(lds, gb, PROJ + r0 * NPAD + PC_MQ + hm * 128, NPAD, (const bf16_t*)(p.ws + WS_CMK) + (size_t)(sq * MEMT) * 512 + hm * 128, (const bf16_t*)(p.ws + WS_CMV) + (size_t)(sq * MEMT) * 512 + hm * 128, 512,
;                                  4, 0, DTOK, 0.f, PROJ + r0 * NPAD + PC_GM + hm * 128, NPAD, MIX + r0 * 2048 + 1536 + hm * 128, 2048); } })
.LBB0_883:
	s_and_saveexec_b64 s[16:17], s[0:1]
	s_cbranch_execz .Lmem_poll_end
	s_mov_b32 s5, 0x8000
	v_mov_b32_e32 v2, 0

; #define GROUP_LOOP(qi, total, ...) for (int gi_ = 0;; ++gi_) { if (threadIdx.x == 0) ctlw[22 + (gi_ & 1)] = __hip_atomic_fetch_add(qbase + 64 * (qi), 1u, __ATOMIC_RELAXED, __HIP_MEMORY_SCOPE_AGENT); \
;         group_bar(gb, lane); const int u = (int)ctlw[22 + (gi_ & 1)]; if (u >= (total)) break; __VA_ARGS__ }
; template <int MASK> __device__ __forceinline__ void phase3(const Params& p, LAS unsigned char* lds, volatile LAS unsigned* ctlw, int qset) {
;     ...
;             GROUP_LOOP(3, U_MEMP + U_MEMS, {
;                 if (u < U_MEMP) { const int hm = u & 3, qb = (u >> 2) & 15, b = u >> 6; const size_t r0 = (size_t)(b * SEQ + qb * 128);
;                     attn_unit<1>(lds, gb, PROJ + r0 * NPAD + PC_MQ + hm * 128, NPAD, (const bf16_t*)(p.ws + WS_MKN) + (size_t)(b * MEMT) * 512 + hm * 128, (const bf16_t*)(p.ws + WS_MVB) + (size_t)(b * MEMT) * 512 + hm * 128, 512,
;                                  4, 0, 128, 0.f, PROJ + r0 * NPAD + PC_GM + hm * 128, NPAD, MIX + r0 * 2048 + 1536 + hm * 128, 2048); }
;                 else { const int v = u - U_MEMP, hm = v & 3, sq = v >> 2; const size_t r0 = (size_t)(MP + sq * DTOK);
;                     attn_unit<1>(lds, gb, PROJ + r0 * NPAD + PC_MQ + hm * 128, NPAD, (const bf16_t*)(p.ws + WS_CMK) + (size_t)(sq * MEMT) * 512 + hm * 128, (const bf16_t*)(p.ws + WS_CMV) + (size_t)(sq * MEMT) * 512 + hm * 128, 512,
;                                  4, 0, DTOK, 0.f, PROJ + r0 * NPAD + PC_GM + hm * 128, NPAD, MIX + r0 * 2048 + 1536 + hm * 128, 2048); } })
.Lmem_poll_end:
	s_or_b64 exec, exec, s[16:17]
	s_add_u32 s26, s90, 0xd700000
	s_addc_u32 s27, s91, 0
	s_add_u32 s29, s90, 0xda00000
	s_addc_u32 s30, s91, 0
	s_add_u32 s31, s90, 0xd300000
	s_addc_u32 s34, s91, 0
	s_add_u32 s35, s90, 0xd500000
	s_addc_u32 s44, s91, 0
	s_add_i32 s46, 0, 0x27e50
	s_mov_b32 s7, 0
	s_waitcnt vmcnt(4)
	v_mov_b32_e32 v147, 0
	v_mov_b32_e32 v1, s46
	s_movk_i32 s47, 0x11f
	s_movk_i32 s50, 0x3600
	s_movk_i32 s51, 0x70
	s_mov_b32 s53, 0xfffff0
	s_movk_i32 s54, 0xc0
	s_movk_i32 s55, 0x60
	s_movk_i32 s62, 0x80
	s_movk_i32 s63, 0xa0
	s_movk_i32 s64, 0xe0
	s_movk_i32 s65, 0x118
	s_mov_b64 s[8:9], 0x4000
	s_mov_b64 s[10:11], 0x8000
	s_mov_b64 s[12:13], 0xc000
	s_mov_b64 s[14:15], 0xc00
	s_mov_b32 s66, 0
	s_branch .LBB0_886
